# P1 in-proj epilogue too: all 8 sum-of-squares loads issued at the epilogue top, per-row-group vmcnt waits dropped
# baseline (speedup 1.0000x reference)
; __device__ __forceinline__ unsigned cvt_pk_bf16(float lo, float hi) { unsigned r; asm volatile("v_cvt_pk_bf16_f32 %0, %1, %2" : "=v"(r) : "v"(lo), "v"(hi)); return r; }
;     __device__ __forceinline__ void operator()(const f32x4 (&acc)[2][2][4][2], const Unit& u, int wr, int wc, int fr, int fq) const {
;     ...
;             for (int m = 0; m < 4; ++m) { const int row = row0 + ai * HALF + m * 16;
;                 const float rs = __builtin_amdgcn_rsqf(ssq[row] * (1.0f / 1024.0f) + 1e-6f);
;                 const int b = row >> 12, tl = row & 4095, tile = tl >> 5, r = tl & 31;
; #pragma unroll
;                 for (int bj = 0; bj < 2; ++bj) { const int cc = colt - part * 1280 + bj * HALF + wc * 32 + 8 * fq, hd = cc / 80, ch8 = cc - hd * 80;
;                     const f32x4 v0 = acc[ai][bj][m][0] * rs, v1 = acc[ai][bj][m][1] * rs;
;                     bf16_t* p = base + ((size_t)((((b * 128 + tile) * 16 + hd) * 10 + (ch8 >> 3)) * 64 + r) << 2);
;                     *(unsigned long long*)p = (unsigned long long)cvt_pk_bf16(v0[0], v0[1]) | ((unsigned long long)cvt_pk_bf16(v0[2], v0[3]) << 32);
;                     *(unsigned long long*)(p + 128) = (unsigned long long)cvt_pk_bf16(v1[0], v1[1]) | ((unsigned long long)cvt_pk_bf16(v1[2], v1[3]) << 32); }
;                 asm volatile("" ::: "memory"); }
.LBB0_191:
	s_lshl_b32 s25, s34, 8
	s_add_i32 s27, s25, s77
	v_or_b32_e32 v144, s27, v149
	v_ashrrev_i32_e32 v145, 31, v144
	v_lshl_add_u64 v[146:147], v[144:145], 2, s[18:19]
	global_load_dword v159, v[146:147], off
	global_load_dword v237, v[146:147], off offset:64
	global_load_dword v238, v[146:147], off offset:128
	global_load_dword v239, v[146:147], off offset:192
	global_load_dword v240, v[146:147], off offset:512
	global_load_dword v241, v[146:147], off offset:576
	global_load_dword v242, v[146:147], off offset:640
	global_load_dword v243, v[146:147], off offset:704
	s_lshl_b32 s25, s35, 8
	s_cmp_gt_i32 s35, 4
	s_cselect_b32 s34, 0x2800000, 0
	s_cselect_b32 s36, 0xfffffb00, 0
	s_add_u32 s34, s75, s34
	s_addc_u32 s35, s76, 0
	s_add_i32 s36, s36, s25
	s_ashr_i32 s25, s27, 5
	s_lshr_b32 s27, s27, 5
	v_or_b32_e32 v148, s36, v153
	s_and_b32 s36, s25, 0xffffff80
	s_and_b32 s27, s27, 0x7e
	v_mul_hi_i32 v145, v148, s74
	v_or_b32_e32 v150, 0x80, v148
	s_or_b32 s27, s27, s36
	v_lshrrev_b32_e32 v158, 31, v145
	v_ashrrev_i32_e32 v145, 5, v145
	v_mul_hi_i32 v160, v150, s74
	s_lshl_b32 s27, s27, 4
	v_add_u32_e32 v158, v145, v158
	v_lshrrev_b32_e32 v145, 31, v160
	v_ashrrev_i32_e32 v162, 5, v160
	v_mad_u64_u32 v[160:161], s[36:37], v158, s84, v[148:149]
	v_add_u32_e32 v148, s27, v158
	v_add_u32_e32 v145, v162, v145
	v_mul_lo_u32 v162, v148, 10
	v_ashrrev_i32_e32 v148, 3, v160
	v_mad_u64_u32 v[160:161], s[36:37], v145, s84, v[150:151]
	v_add_u32_e32 v150, s27, v145
	v_mul_lo_u32 v161, v150, 10
	v_ashrrev_i32_e32 v150, 3, v160
	v_add_lshl_u32 v165, v148, v162, 6
	v_add_lshl_u32 v166, v150, v161, 6
	v_or_b32_e32 v160, v165, v149
	v_or_b32_e32 v162, v166, v149
	v_ashrrev_i32_e32 v161, 31, v160
	v_ashrrev_i32_e32 v163, 31, v162
	v_lshl_add_u64 v[160:161], v[160:161], 3, s[34:35]
	v_lshl_add_u64 v[162:163], v[162:163], 3, s[34:35]
	s_andn2_b64 vcc, exec, s[2:3]
	s_mov_b64 s[2:3], -1
	s_waitcnt vmcnt(0)
	v_fmamk_f32 v159, v159, 0x3a800000, v157
	v_rsq_f32_e32 v164, v159
	s_nop 0
	v_pk_mul_f32 v[124:125], v[124:125], v[164:165] op_sel_hi:[1,0]
	v_pk_mul_f32 v[120:121], v[120:121], v[164:165] op_sel_hi:[1,0]
	v_pk_mul_f32 v[116:117], v[116:117], v[164:165] op_sel_hi:[1,0]
	v_pk_mul_f32 v[112:113], v[112:113], v[164:165] op_sel_hi:[1,0]
	v_pk_mul_f32 v[126:127], v[126:127], v[164:165] op_sel_hi:[1,0]
	v_pk_mul_f32 v[122:123], v[122:123], v[164:165] op_sel_hi:[1,0]
	v_pk_mul_f32 v[118:119], v[118:119], v[164:165] op_sel_hi:[1,0]
	v_pk_mul_f32 v[114:115], v[114:115], v[164:165] op_sel_hi:[1,0]
	v_cvt_pk_bf16_f32 v124, v124, v125
	v_cvt_pk_bf16_f32 v125, v126, v127
	global_store_dwordx2 v[160:161], v[124:125], off
	v_cvt_pk_bf16_f32 v120, v120, v121
	v_cvt_pk_bf16_f32 v121, v122, v123
	global_store_dwordx2 v[160:161], v[120:121], off offset:256
	v_cvt_pk_bf16_f32 v116, v116, v117
	v_cvt_pk_bf16_f32 v117, v118, v119
	global_store_dwordx2 v[162:163], v[116:117], off
	v_cvt_pk_bf16_f32 v112, v112, v113
	v_cvt_pk_bf16_f32 v113, v114, v115
	global_store_dwordx2 v[162:163], v[112:113], off offset:256
	s_nop 0
	v_or_b32_e32 v112, 32, v144
	v_ashrrev_i32_e32 v113, 31, v112
	v_lshl_add_u64 v[114:115], v[112:113], 2, s[18:19]
	v_or_b32_e32 v116, v165, v152
	v_or_b32_e32 v118, v166, v152
	v_ashrrev_i32_e32 v117, 31, v116
	v_lshl_add_u64 v[116:117], v[116:117], 3, s[34:35]
	s_nop 0
	v_fmamk_f32 v113, v237, 0x3a800000, v157
	v_rsq_f32_e32 v120, v113
	v_ashrrev_i32_e32 v119, 31, v118
	v_lshl_add_u64 v[118:119], v[118:119], 3, s[34:35]
	v_pk_mul_f32 v[108:109], v[108:109], v[120:121] op_sel_hi:[1,0]
	v_pk_mul_f32 v[104:105], v[104:105], v[120:121] op_sel_hi:[1,0]
	v_pk_mul_f32 v[100:101], v[100:101], v[120:121] op_sel_hi:[1,0]
	v_pk_mul_f32 v[96:97], v[96:97], v[120:121] op_sel_hi:[1,0]
	v_pk_mul_f32 v[110:111], v[110:111], v[120:121] op_sel_hi:[1,0]
	v_pk_mul_f32 v[106:107], v[106:107], v[120:121] op_sel_hi:[1,0]
	v_pk_mul_f32 v[102:103], v[102:103], v[120:121] op_sel_hi:[1,0]
	v_pk_mul_f32 v[98:99], v[98:99], v[120:121] op_sel_hi:[1,0]
	v_cvt_pk_bf16_f32 v108, v108, v109
	v_cvt_pk_bf16_f32 v109, v110, v111
	global_store_dwordx2 v[116:117], v[108:109], off
	v_cvt_pk_bf16_f32 v104, v104, v105
	v_cvt_pk_bf16_f32 v105, v106, v107
	global_store_dwordx2 v[116:117], v[104:105], off offset:256
	v_cvt_pk_bf16_f32 v100, v100, v101
	v_cvt_pk_bf16_f32 v101, v102, v103
	global_store_dwordx2 v[118:119], v[100:101], off
	v_cvt_pk_bf16_f32 v96, v96, v97
	v_cvt_pk_bf16_f32 v97, v98, v99
	global_store_dwordx2 v[118:119], v[96:97], off offset:256
	s_nop 0
	v_or_b32_e32 v96, 48, v144
	v_ashrrev_i32_e32 v97, 31, v96
	v_lshrrev_b32_e32 v100, 5, v112
	v_lshl_add_u64 v[98:99], v[96:97], 2, s[18:19]
	v_mov_b32_e32 v97, s25
	v_bfi_b32 v100, s86, v100, v97
	v_lshlrev_b32_e32 v100, 4, v100
	v_add_u32_e32 v102, v100, v145
	v_mad_u64_u32 v[102:103], s[36:37], v102, 10, v[150:151]
	v_add_u32_e32 v101, v100, v158
	v_mad_u64_u32 v[100:101], s[36:37], v101, 10, v[148:149]
	v_lshl_or_b32 v100, v100, 6, v149
	v_lshl_or_b32 v102, v102, 6, v149
	v_ashrrev_i32_e32 v101, 31, v100
	v_lshl_add_u64 v[100:101], v[100:101], 3, s[34:35]
	s_nop 0
	v_fmamk_f32 v103, v238, 0x3a800000, v157
	v_rsq_f32_e32 v104, v103
	v_ashrrev_i32_e32 v103, 31, v102
	v_lshl_add_u64 v[102:103], v[102:103], 3, s[34:35]
	v_pk_mul_f32 v[92:93], v[92:93], v[104:105] op_sel_hi:[1,0]
	v_pk_mul_f32 v[88:89], v[88:89], v[104:105] op_sel_hi:[1,0]
	v_pk_mul_f32 v[84:85], v[84:85], v[104:105] op_sel_hi:[1,0]
	v_pk_mul_f32 v[80:81], v[80:81], v[104:105] op_sel_hi:[1,0]
	v_pk_mul_f32 v[94:95], v[94:95], v[104:105] op_sel_hi:[1,0]
	v_pk_mul_f32 v[90:91], v[90:91], v[104:105] op_sel_hi:[1,0]
	v_pk_mul_f32 v[86:87], v[86:87], v[104:105] op_sel_hi:[1,0]
; __device__ __forceinline__ unsigned cvt_pk_bf16(float lo, float hi) { unsigned r; asm volatile("v_cvt_pk_bf16_f32 %0, %1, %2" : "=v"(r) : "v"(lo), "v"(hi)); return r; }
;     __device__ __forceinline__ void operator()(const f32x4 (&acc)[2][2][4][2], const Unit& u, int wr, int wc, int fr, int fq) const {
;     ...
;             for (int m = 0; m < 4; ++m) { const int row = row0 + ai * HALF + m * 16;
;                 const float rs = __builtin_amdgcn_rsqf(ssq[row] * (1.0f / 1024.0f) + 1e-6f);
;                 const int b = row >> 12, tl = row & 4095, tile = tl >> 5, r = tl & 31;
; #pragma unroll
;                 for (int bj = 0; bj < 2; ++bj) { const int cc = colt - part * 1280 + bj * HALF + wc * 32 + 8 * fq, hd = cc / 80, ch8 = cc - hd * 80;
;                     const f32x4 v0 = acc[ai][bj][m][0] * rs, v1 = acc[ai][bj][m][1] * rs;
;                     bf16_t* p = base + ((size_t)((((b * 128 + tile) * 16 + hd) * 10 + (ch8 >> 3)) * 64 + r) << 2);
;                     *(unsigned long long*)p = (unsigned long long)cvt_pk_bf16(v0[0], v0[1]) | ((unsigned long long)cvt_pk_bf16(v0[2], v0[3]) << 32);
;                     *(unsigned long long*)(p + 128) = (unsigned long long)cvt_pk_bf16(v1[0], v1[1]) | ((unsigned long long)cvt_pk_bf16(v1[2], v1[3]) << 32); }
;                 asm volatile("" ::: "memory"); }
	v_pk_mul_f32 v[82:83], v[82:83], v[104:105] op_sel_hi:[1,0]
	v_cvt_pk_bf16_f32 v92, v92, v93
	v_cvt_pk_bf16_f32 v93, v94, v95
	global_store_dwordx2 v[100:101], v[92:93], off
	v_cvt_pk_bf16_f32 v88, v88, v89
	v_cvt_pk_bf16_f32 v89, v90, v91
	global_store_dwordx2 v[100:101], v[88:89], off offset:256
	v_cvt_pk_bf16_f32 v84, v84, v85
	v_cvt_pk_bf16_f32 v85, v86, v87
	global_store_dwordx2 v[102:103], v[84:85], off
	v_cvt_pk_bf16_f32 v80, v80, v81
	v_cvt_pk_bf16_f32 v81, v82, v83
	global_store_dwordx2 v[102:103], v[80:81], off offset:256
	s_nop 0
	v_lshrrev_b32_e32 v80, 5, v96
	v_bfi_b32 v80, s86, v80, v97
	v_lshlrev_b32_e32 v80, 4, v80
	v_add_u32_e32 v82, v80, v145
	v_mad_u64_u32 v[82:83], s[36:37], v82, 10, v[150:151]
	v_add_u32_e32 v81, v80, v158
	v_mad_u64_u32 v[80:81], s[36:37], v81, 10, v[148:149]
	v_lshl_or_b32 v80, v80, 6, v152
	v_lshl_or_b32 v82, v82, 6, v152
	v_ashrrev_i32_e32 v81, 31, v80
	v_lshl_add_u64 v[80:81], v[80:81], 3, s[34:35]
	s_nop 0
	v_fmamk_f32 v83, v239, 0x3a800000, v157
	v_rsq_f32_e32 v84, v83
	v_ashrrev_i32_e32 v83, 31, v82
	v_lshl_add_u64 v[82:83], v[82:83], 3, s[34:35]
	v_pk_mul_f32 v[76:77], v[76:77], v[84:85] op_sel_hi:[1,0]
	v_pk_mul_f32 v[72:73], v[72:73], v[84:85] op_sel_hi:[1,0]
	v_pk_mul_f32 v[68:69], v[68:69], v[84:85] op_sel_hi:[1,0]
	v_pk_mul_f32 v[64:65], v[64:65], v[84:85] op_sel_hi:[1,0]
	v_pk_mul_f32 v[78:79], v[78:79], v[84:85] op_sel_hi:[1,0]
	v_pk_mul_f32 v[74:75], v[74:75], v[84:85] op_sel_hi:[1,0]
	v_pk_mul_f32 v[70:71], v[70:71], v[84:85] op_sel_hi:[1,0]
	v_pk_mul_f32 v[66:67], v[66:67], v[84:85] op_sel_hi:[1,0]
	v_cvt_pk_bf16_f32 v76, v76, v77
	v_cvt_pk_bf16_f32 v77, v78, v79
	global_store_dwordx2 v[80:81], v[76:77], off
	v_cvt_pk_bf16_f32 v72, v72, v73
	v_cvt_pk_bf16_f32 v73, v74, v75
	global_store_dwordx2 v[80:81], v[72:73], off offset:256
	v_cvt_pk_bf16_f32 v68, v68, v69
	v_cvt_pk_bf16_f32 v69, v70, v71
	global_store_dwordx2 v[82:83], v[68:69], off
	v_cvt_pk_bf16_f32 v64, v64, v65
	v_cvt_pk_bf16_f32 v65, v66, v67
	global_store_dwordx2 v[82:83], v[64:65], off offset:256
	s_nop 0
	v_add_u32_e32 v64, 0x80, v144
	v_ashrrev_i32_e32 v69, 5, v64
	v_lshrrev_b32_e32 v64, 5, v64
	v_and_b32_e32 v70, 0xffffff80, v69
	v_and_or_b32 v64, v64, s85, v70
	v_lshlrev_b32_e32 v64, 4, v64
	v_add_u32_e32 v66, v64, v145
	v_mad_u64_u32 v[66:67], s[36:37], v66, 10, v[150:151]
	v_add_u32_e32 v65, v64, v158
	v_mad_u64_u32 v[64:65], s[36:37], v65, 10, v[148:149]
	v_lshl_or_b32 v64, v64, 6, v149
	v_lshl_or_b32 v66, v66, 6, v149
	v_ashrrev_i32_e32 v65, 31, v64
	v_lshl_add_u64 v[64:65], v[64:65], 3, s[34:35]
	s_nop 0
	v_fmamk_f32 v67, v240, 0x3a800000, v157
	v_rsq_f32_e32 v68, v67
	v_ashrrev_i32_e32 v67, 31, v66
	v_lshl_add_u64 v[66:67], v[66:67], 3, s[34:35]
	v_pk_mul_f32 v[60:61], v[60:61], v[68:69] op_sel_hi:[1,0]
	v_pk_mul_f32 v[56:57], v[56:57], v[68:69] op_sel_hi:[1,0]
	v_pk_mul_f32 v[52:53], v[52:53], v[68:69] op_sel_hi:[1,0]
	v_pk_mul_f32 v[48:49], v[48:49], v[68:69] op_sel_hi:[1,0]
	v_pk_mul_f32 v[62:63], v[62:63], v[68:69] op_sel_hi:[1,0]
	v_pk_mul_f32 v[58:59], v[58:59], v[68:69] op_sel_hi:[1,0]
	v_pk_mul_f32 v[54:55], v[54:55], v[68:69] op_sel_hi:[1,0]
	v_pk_mul_f32 v[50:51], v[50:51], v[68:69] op_sel_hi:[1,0]
	v_cvt_pk_bf16_f32 v60, v60, v61
	v_cvt_pk_bf16_f32 v61, v62, v63
	global_store_dwordx2 v[64:65], v[60:61], off
	v_cvt_pk_bf16_f32 v56, v56, v57
	v_cvt_pk_bf16_f32 v57, v58, v59
	global_store_dwordx2 v[64:65], v[56:57], off offset:256
	v_cvt_pk_bf16_f32 v52, v52, v53
	v_cvt_pk_bf16_f32 v53, v54, v55
	global_store_dwordx2 v[66:67], v[52:53], off
	v_cvt_pk_bf16_f32 v48, v48, v49
	v_cvt_pk_bf16_f32 v49, v50, v51
	global_store_dwordx2 v[66:67], v[48:49], off offset:256
	s_nop 0
	v_add_u32_e32 v48, 0x90, v144
	v_lshrrev_b32_e32 v48, 5, v48
	v_and_or_b32 v48, v48, s85, v70
	v_lshlrev_b32_e32 v48, 4, v48
	v_add_u32_e32 v50, v48, v145
	v_mad_u64_u32 v[50:51], s[36:37], v50, 10, v[150:151]
	v_add_u32_e32 v49, v48, v158
	v_mad_u64_u32 v[48:49], s[36:37], v49, 10, v[148:149]
	v_lshl_or_b32 v48, v48, 6, v152
	v_lshl_or_b32 v50, v50, 6, v152
	v_ashrrev_i32_e32 v49, 31, v48
	v_lshl_add_u64 v[48:49], v[48:49], 3, s[34:35]
	s_nop 0
	v_fmamk_f32 v51, v241, 0x3a800000, v157
	v_rsq_f32_e32 v52, v51
; __device__ __forceinline__ unsigned cvt_pk_bf16(float lo, float hi) { unsigned r; asm volatile("v_cvt_pk_bf16_f32 %0, %1, %2" : "=v"(r) : "v"(lo), "v"(hi)); return r; }
;     __device__ __forceinline__ void operator()(const f32x4 (&acc)[2][2][4][2], const Unit& u, int wr, int wc, int fr, int fq) const {
;     ...
;             for (int m = 0; m < 4; ++m) { const int row = row0 + ai * HALF + m * 16;
;                 const float rs = __builtin_amdgcn_rsqf(ssq[row] * (1.0f / 1024.0f) + 1e-6f);
;                 const int b = row >> 12, tl = row & 4095, tile = tl >> 5, r = tl & 31;
; #pragma unroll
;                 for (int bj = 0; bj < 2; ++bj) { const int cc = colt - part * 1280 + bj * HALF + wc * 32 + 8 * fq, hd = cc / 80, ch8 = cc - hd * 80;
;                     const f32x4 v0 = acc[ai][bj][m][0] * rs, v1 = acc[ai][bj][m][1] * rs;
;                     bf16_t* p = base + ((size_t)((((b * 128 + tile) * 16 + hd) * 10 + (ch8 >> 3)) * 64 + r) << 2);
;                     *(unsigned long long*)p = (unsigned long long)cvt_pk_bf16(v0[0], v0[1]) | ((unsigned long long)cvt_pk_bf16(v0[2], v0[3]) << 32);
;                     *(unsigned long long*)(p + 128) = (unsigned long long)cvt_pk_bf16(v1[0], v1[1]) | ((unsigned long long)cvt_pk_bf16(v1[2], v1[3]) << 32); }
;                 asm volatile("" ::: "memory"); }
	v_ashrrev_i32_e32 v51, 31, v50
	v_lshl_add_u64 v[50:51], v[50:51], 3, s[34:35]
	v_pk_mul_f32 v[44:45], v[44:45], v[52:53] op_sel_hi:[1,0]
	v_pk_mul_f32 v[40:41], v[40:41], v[52:53] op_sel_hi:[1,0]
	v_pk_mul_f32 v[36:37], v[36:37], v[52:53] op_sel_hi:[1,0]
	v_pk_mul_f32 v[32:33], v[32:33], v[52:53] op_sel_hi:[1,0]
	v_pk_mul_f32 v[46:47], v[46:47], v[52:53] op_sel_hi:[1,0]
	v_pk_mul_f32 v[42:43], v[42:43], v[52:53] op_sel_hi:[1,0]
	v_pk_mul_f32 v[38:39], v[38:39], v[52:53] op_sel_hi:[1,0]
	v_pk_mul_f32 v[34:35], v[34:35], v[52:53] op_sel_hi:[1,0]
	v_cvt_pk_bf16_f32 v44, v44, v45
	v_cvt_pk_bf16_f32 v45, v46, v47
	global_store_dwordx2 v[48:49], v[44:45], off
	v_cvt_pk_bf16_f32 v40, v40, v41
	v_cvt_pk_bf16_f32 v41, v42, v43
	global_store_dwordx2 v[48:49], v[40:41], off offset:256
	v_cvt_pk_bf16_f32 v36, v36, v37
	v_cvt_pk_bf16_f32 v37, v38, v39
	global_store_dwordx2 v[50:51], v[36:37], off
	v_cvt_pk_bf16_f32 v32, v32, v33
	v_cvt_pk_bf16_f32 v33, v34, v35
	global_store_dwordx2 v[50:51], v[32:33], off offset:256
	s_nop 0
	v_add_u32_e32 v32, 0xa0, v144
	v_lshrrev_b32_e32 v32, 5, v32
	v_bfi_b32 v32, s86, v32, v69
	v_lshlrev_b32_e32 v32, 4, v32
	v_add_u32_e32 v34, v32, v145
	v_mad_u64_u32 v[34:35], s[36:37], v34, 10, v[150:151]
	v_add_u32_e32 v33, v32, v158
	v_mad_u64_u32 v[32:33], s[36:37], v33, 10, v[148:149]
	v_lshl_or_b32 v32, v32, 6, v149
	v_lshl_or_b32 v34, v34, 6, v149
	v_ashrrev_i32_e32 v33, 31, v32
	v_lshl_add_u64 v[32:33], v[32:33], 3, s[34:35]
	s_nop 0
	v_fmamk_f32 v35, v242, 0x3a800000, v157
	v_rsq_f32_e32 v36, v35
	v_ashrrev_i32_e32 v35, 31, v34
	v_lshl_add_u64 v[34:35], v[34:35], 3, s[34:35]
	v_pk_mul_f32 v[28:29], v[28:29], v[36:37] op_sel_hi:[1,0]
	v_pk_mul_f32 v[24:25], v[24:25], v[36:37] op_sel_hi:[1,0]
	v_pk_mul_f32 v[20:21], v[20:21], v[36:37] op_sel_hi:[1,0]
	v_pk_mul_f32 v[16:17], v[16:17], v[36:37] op_sel_hi:[1,0]
	v_pk_mul_f32 v[30:31], v[30:31], v[36:37] op_sel_hi:[1,0]
	v_pk_mul_f32 v[26:27], v[26:27], v[36:37] op_sel_hi:[1,0]
	v_pk_mul_f32 v[22:23], v[22:23], v[36:37] op_sel_hi:[1,0]
	v_pk_mul_f32 v[18:19], v[18:19], v[36:37] op_sel_hi:[1,0]
	v_cvt_pk_bf16_f32 v28, v28, v29
	v_cvt_pk_bf16_f32 v29, v30, v31
	global_store_dwordx2 v[32:33], v[28:29], off
	v_cvt_pk_bf16_f32 v24, v24, v25
	v_cvt_pk_bf16_f32 v25, v26, v27
	global_store_dwordx2 v[32:33], v[24:25], off offset:256
	v_cvt_pk_bf16_f32 v20, v20, v21
	v_cvt_pk_bf16_f32 v21, v22, v23
	global_store_dwordx2 v[34:35], v[20:21], off
	v_cvt_pk_bf16_f32 v16, v16, v17
	v_cvt_pk_bf16_f32 v17, v18, v19
	global_store_dwordx2 v[34:35], v[16:17], off offset:256
	s_nop 0
	v_add_u32_e32 v16, 0xb0, v144
	v_lshrrev_b32_e32 v16, 5, v16
	v_bfi_b32 v16, s86, v16, v69
	v_lshlrev_b32_e32 v16, 4, v16
	v_add_u32_e32 v18, v16, v145
	v_mad_u64_u32 v[18:19], s[36:37], v18, 10, v[150:151]
	v_add_u32_e32 v17, v16, v158
	v_mad_u64_u32 v[16:17], s[36:37], v17, 10, v[148:149]
	v_lshl_or_b32 v16, v16, 6, v152
	v_lshl_or_b32 v18, v18, 6, v152
	v_ashrrev_i32_e32 v17, 31, v16
	v_lshl_add_u64 v[16:17], v[16:17], 3, s[34:35]
	s_nop 0
	v_fmamk_f32 v19, v243, 0x3a800000, v157
	v_rsq_f32_e32 v20, v19
	v_ashrrev_i32_e32 v19, 31, v18
	v_lshl_add_u64 v[18:19], v[18:19], 3, s[34:35]
	v_pk_mul_f32 v[12:13], v[12:13], v[20:21] op_sel_hi:[1,0]
	v_pk_mul_f32 v[8:9], v[8:9], v[20:21] op_sel_hi:[1,0]
	v_pk_mul_f32 v[4:5], v[4:5], v[20:21] op_sel_hi:[1,0]
	v_pk_mul_f32 v[0:1], v[0:1], v[20:21] op_sel_hi:[1,0]
	v_pk_mul_f32 v[14:15], v[14:15], v[20:21] op_sel_hi:[1,0]
	v_pk_mul_f32 v[10:11], v[10:11], v[20:21] op_sel_hi:[1,0]
	v_pk_mul_f32 v[6:7], v[6:7], v[20:21] op_sel_hi:[1,0]
	v_pk_mul_f32 v[2:3], v[2:3], v[20:21] op_sel_hi:[1,0]
	v_cvt_pk_bf16_f32 v12, v12, v13
	v_cvt_pk_bf16_f32 v13, v14, v15
	global_store_dwordx2 v[16:17], v[12:13], off
	v_cvt_pk_bf16_f32 v8, v8, v9
	v_cvt_pk_bf16_f32 v9, v10, v11
	global_store_dwordx2 v[16:17], v[8:9], off offset:256
	v_cvt_pk_bf16_f32 v4, v4, v5
	v_cvt_pk_bf16_f32 v5, v6, v7
	global_store_dwordx2 v[18:19], v[4:5], off
	v_cvt_pk_bf16_f32 v0, v0, v1
	v_cvt_pk_bf16_f32 v1, v2, v3
	global_store_dwordx2 v[18:19], v[0:1], off offset:256
	s_cbranch_vccnz .LBB0_184
	s_andn2_b64 vcc, exec, s[8:9]
	s_cbranch_vccnz .LBB0_183
	s_barrier
	s_branch .LBB0_183
